# diff attention: exps and row sums of key groups 1-3 issued inside the P*V MFMA gaps (register renames, same arithmetic)
# speedup vs baseline: 1.0061x; 1.0034x over previous
; template <int DVT, bool FOX>
; DI void attn_step(const char* kb, const bf16x8 (&qf)[4], f32x16 (&o)[DVT], float& m, float& l, const bool diag, const int j, const int tq, const int r, const int hh) {
;     ...
;   f32x2 ls2 = {0.f, 0.f};
; #pragma unroll
;   for (int kt = 0; kt < 2; ++kt)
; #pragma unroll
;     for (int i = 0; i < 8; ++i) {
;       f32x2 pv = {__builtin_amdgcn_exp2f(st[kt][2 * i]), __builtin_amdgcn_exp2f(st[kt][2 * i + 1])};
;       st[kt][2 * i] = pv[0]; st[kt][2 * i + 1] = pv[1];
;       ls2 = ls2 + pv;
;     }
;   l += ls2[0] + ls2[1];
;   __builtin_amdgcn_sched_barrier(0);
;     ...
;   A_PVGROUP(0, va, vn); A_PVGROUP(1, vn, va); A_PVGROUP(2, va, vn); A_PVGROUP(3, vn, va);
.LBB0_645:
	v_exp_f32_e32 v110, v170
	v_exp_f32_e32 v111, v171
	v_exp_f32_e32 v170, v172
	v_exp_f32_e32 v171, v173
	v_exp_f32_e32 v172, v174
	v_exp_f32_e32 v173, v175
	v_exp_f32_e32 v174, v176
	v_exp_f32_e32 v175, v177
	ds_read_b128 v[228:231], v184 offset:9248
	ds_read_b128 v[232:235], v184 offset:13856
	ds_read_b128 v[236:239], v184 offset:18464
	ds_read_b128 v[240:243], v184 offset:23072
	v_pk_add_f32 v[88:89], v[110:111], 0 op_sel_hi:[1,0]
	s_nop 0
	v_pk_add_f32 v[88:89], v[170:171], v[88:89]
	s_nop 0
	v_pk_add_f32 v[88:89], v[172:173], v[88:89]
	s_nop 0
	v_pk_add_f32 v[88:89], v[174:175], v[88:89]
	v_cvt_pk_bf16_f32 v244, v110, v111
	v_cvt_pk_bf16_f32 v245, v170, v171
	v_cvt_pk_bf16_f32 v246, v172, v173
	v_cvt_pk_bf16_f32 v247, v174, v175
	s_waitcnt lgkmcnt(7)
	s_nop 0
	v_mfma_f32_32x32x16_bf16 v[64:79], v[152:155], v[244:247], v[64:79]
	v_exp_f32_e32 v102, v102
	v_exp_f32_e32 v103, v103
	s_waitcnt lgkmcnt(6)
	v_mfma_f32_32x32x16_bf16 v[48:63], v[10:13], v[244:247], v[48:63]
	v_exp_f32_e32 v104, v104
	v_exp_f32_e32 v105, v105
	v_pk_add_f32 v[88:89], v[102:103], v[88:89]
	s_waitcnt lgkmcnt(5)
	v_mfma_f32_32x32x16_bf16 v[32:47], v[6:9], v[244:247], v[32:47]
	v_exp_f32_e32 v106, v106
	v_exp_f32_e32 v107, v107
	v_pk_add_f32 v[88:89], v[104:105], v[88:89]
	s_waitcnt lgkmcnt(4)
	v_mfma_f32_32x32x16_bf16 v[16:31], v[2:5], v[244:247], v[16:31]
	v_exp_f32_e32 v108, v108
	v_exp_f32_e32 v109, v109
	v_pk_add_f32 v[88:89], v[106:107], v[88:89]
	ds_read_b128 v[2:5], v184 offset:9280
	ds_read_b128 v[6:9], v184 offset:13888
	ds_read_b128 v[10:13], v184 offset:18496
	ds_read_b128 v[218:221], v184 offset:23104
	v_pk_add_f32 v[88:89], v[108:109], v[88:89]
	v_cvt_pk_bf16_f32 v248, v102, v103
	v_cvt_pk_bf16_f32 v249, v104, v105
	v_cvt_pk_bf16_f32 v250, v106, v107
	v_cvt_pk_bf16_f32 v251, v108, v109
	s_waitcnt lgkmcnt(7)
	s_nop 0
	v_mfma_f32_32x32x16_bf16 v[64:79], v[228:231], v[248:251], v[64:79]
	v_exp_f32_e32 v176, v96
	v_exp_f32_e32 v177, v97
	s_waitcnt lgkmcnt(6)
	v_mfma_f32_32x32x16_bf16 v[48:63], v[232:235], v[248:251], v[48:63]
	v_exp_f32_e32 v186, v98
	v_exp_f32_e32 v187, v99
	v_pk_add_f32 v[88:89], v[176:177], v[88:89]
	s_waitcnt lgkmcnt(5)
	v_mfma_f32_32x32x16_bf16 v[32:47], v[236:239], v[248:251], v[32:47]
	v_exp_f32_e32 v188, v100
	v_exp_f32_e32 v189, v101
	v_pk_add_f32 v[88:89], v[186:187], v[88:89]
	s_waitcnt lgkmcnt(4)
	v_mfma_f32_32x32x16_bf16 v[16:31], v[240:243], v[248:251], v[16:31]
	v_exp_f32_e32 v190, v86
	v_exp_f32_e32 v191, v87
	v_pk_add_f32 v[88:89], v[188:189], v[88:89]
	ds_read_b128 v[228:231], v184 offset:9312
	ds_read_b128 v[232:235], v184 offset:13920
	ds_read_b128 v[236:239], v184 offset:18528
	ds_read_b128 v[240:243], v184 offset:23136
	v_pk_add_f32 v[88:89], v[190:191], v[88:89]
	v_cvt_pk_bf16_f32 v244, v176, v177
	v_cvt_pk_bf16_f32 v245, v186, v187
	v_cvt_pk_bf16_f32 v246, v188, v189
	v_cvt_pk_bf16_f32 v247, v190, v191
	s_waitcnt lgkmcnt(7)
	s_nop 0
	v_mfma_f32_32x32x16_bf16 v[64:79], v[2:5], v[244:247], v[64:79]
	v_exp_f32_e32 v194, v80
	v_exp_f32_e32 v195, v81
	s_waitcnt lgkmcnt(6)
	v_mfma_f32_32x32x16_bf16 v[48:63], v[6:9], v[244:247], v[48:63]
	v_exp_f32_e32 v196, v82
	v_exp_f32_e32 v197, v83
	v_pk_add_f32 v[88:89], v[194:195], v[88:89]
	s_waitcnt lgkmcnt(5)
	v_mfma_f32_32x32x16_bf16 v[32:47], v[10:13], v[244:247], v[32:47]
	v_exp_f32_e32 v198, v84
	v_exp_f32_e32 v199, v85
	v_pk_add_f32 v[88:89], v[196:197], v[88:89]
	s_waitcnt lgkmcnt(4)
	v_mfma_f32_32x32x16_bf16 v[16:31], v[218:221], v[244:247], v[16:31]
	v_exp_f32_e32 v14, v14
	v_exp_f32_e32 v15, v15
	v_pk_add_f32 v[88:89], v[198:199], v[88:89]
	s_nop 0
	v_pk_add_f32 v[88:89], v[14:15], v[88:89]
	v_cvt_pk_bf16_f32 v248, v194, v195
	v_cvt_pk_bf16_f32 v249, v196, v197
	v_cvt_pk_bf16_f32 v250, v198, v199
	v_cvt_pk_bf16_f32 v251, v14, v15
	v_add_f32_e32 v88, v88, v89
	s_waitcnt lgkmcnt(3)
	v_add_f32_e32 v0, v0, v88
	v_mfma_f32_32x32x16_bf16 v[64:79], v[228:231], v[248:251], v[64:79]
	s_waitcnt lgkmcnt(2)
	v_mfma_f32_32x32x16_bf16 v[48:63], v[232:235], v[248:251], v[48:63]
	s_waitcnt lgkmcnt(1)
	v_mfma_f32_32x32x16_bf16 v[32:47], v[236:239], v[248:251], v[32:47]
	s_waitcnt lgkmcnt(0)
	v_mfma_f32_32x32x16_bf16 v[16:31], v[240:243], v[248:251], v[16:31]

; template <int DVT, bool FOX>
; DI void attn_step(const char* kb, const bf16x8 (&qf)[4], f32x16 (&o)[DVT], float& m, float& l, const bool diag, const int j, const int tq, const int r, const int hh) {
;     ...
;   f32x2 ls2 = {0.f, 0.f};
; #pragma unroll
;   for (int kt = 0; kt < 2; ++kt)
; #pragma unroll
;     for (int i = 0; i < 8; ++i) {
;       f32x2 pv = {__builtin_amdgcn_exp2f(st[kt][2 * i]), __builtin_amdgcn_exp2f(st[kt][2 * i + 1])};
;       st[kt][2 * i] = pv[0]; st[kt][2 * i + 1] = pv[1];
;       ls2 = ls2 + pv;
;     }
;   l += ls2[0] + ls2[1];
;   __builtin_amdgcn_sched_barrier(0);
;     ...
;   A_PVGROUP(0, va, vn); A_PVGROUP(1, vn, va); A_PVGROUP(2, va, vn); A_PVGROUP(3, vn, va);
.LBB0_652:
	v_exp_f32_e32 v110, v170
	v_exp_f32_e32 v111, v171
	v_exp_f32_e32 v170, v172
	v_exp_f32_e32 v171, v173
	v_exp_f32_e32 v172, v174
	v_exp_f32_e32 v173, v175
	v_exp_f32_e32 v174, v176
	v_exp_f32_e32 v175, v177
	ds_read_b128 v[228:231], v184 offset:37152
	ds_read_b128 v[232:235], v184 offset:41760
	ds_read_b128 v[236:239], v184 offset:46368
	ds_read_b128 v[240:243], v184 offset:50976
	v_pk_add_f32 v[88:89], v[110:111], 0 op_sel_hi:[1,0]
	s_nop 0
	v_pk_add_f32 v[88:89], v[170:171], v[88:89]
	s_nop 0
	v_pk_add_f32 v[88:89], v[172:173], v[88:89]
	s_nop 0
	v_pk_add_f32 v[88:89], v[174:175], v[88:89]
	v_cvt_pk_bf16_f32 v244, v110, v111
	v_cvt_pk_bf16_f32 v245, v170, v171
	v_cvt_pk_bf16_f32 v246, v172, v173
	v_cvt_pk_bf16_f32 v247, v174, v175
	s_waitcnt lgkmcnt(7)
	s_nop 0
	v_mfma_f32_32x32x16_bf16 v[64:79], v[152:155], v[244:247], v[64:79]
	v_exp_f32_e32 v102, v102
	v_exp_f32_e32 v103, v103
	s_waitcnt lgkmcnt(6)
	v_mfma_f32_32x32x16_bf16 v[48:63], v[10:13], v[244:247], v[48:63]
	v_exp_f32_e32 v104, v104
	v_exp_f32_e32 v105, v105
	v_pk_add_f32 v[88:89], v[102:103], v[88:89]
	s_waitcnt lgkmcnt(5)
	v_mfma_f32_32x32x16_bf16 v[32:47], v[6:9], v[244:247], v[32:47]
	v_exp_f32_e32 v106, v106
	v_exp_f32_e32 v107, v107
	v_pk_add_f32 v[88:89], v[104:105], v[88:89]
	s_waitcnt lgkmcnt(4)
	v_mfma_f32_32x32x16_bf16 v[16:31], v[2:5], v[244:247], v[16:31]
	v_exp_f32_e32 v108, v108
	v_exp_f32_e32 v109, v109
	v_pk_add_f32 v[88:89], v[106:107], v[88:89]
	ds_read_b128 v[2:5], v184 offset:37184
	ds_read_b128 v[6:9], v184 offset:41792
	ds_read_b128 v[10:13], v184 offset:46400
	ds_read_b128 v[218:221], v184 offset:51008
	v_pk_add_f32 v[88:89], v[108:109], v[88:89]
	v_cvt_pk_bf16_f32 v248, v102, v103
	v_cvt_pk_bf16_f32 v249, v104, v105
	v_cvt_pk_bf16_f32 v250, v106, v107
	v_cvt_pk_bf16_f32 v251, v108, v109
	s_waitcnt lgkmcnt(7)
	s_nop 0
	v_mfma_f32_32x32x16_bf16 v[64:79], v[228:231], v[248:251], v[64:79]
	v_exp_f32_e32 v176, v96
	v_exp_f32_e32 v177, v97
	s_waitcnt lgkmcnt(6)
	v_mfma_f32_32x32x16_bf16 v[48:63], v[232:235], v[248:251], v[48:63]
	v_exp_f32_e32 v186, v98
	v_exp_f32_e32 v187, v99
	v_pk_add_f32 v[88:89], v[176:177], v[88:89]
	s_waitcnt lgkmcnt(5)
	v_mfma_f32_32x32x16_bf16 v[32:47], v[236:239], v[248:251], v[32:47]
	v_exp_f32_e32 v188, v100
	v_exp_f32_e32 v189, v101
	v_pk_add_f32 v[88:89], v[186:187], v[88:89]
	s_waitcnt lgkmcnt(4)
	v_mfma_f32_32x32x16_bf16 v[16:31], v[240:243], v[248:251], v[16:31]
	v_exp_f32_e32 v190, v86
	v_exp_f32_e32 v191, v87
	v_pk_add_f32 v[88:89], v[188:189], v[88:89]
	ds_read_b128 v[228:231], v184 offset:37216
	ds_read_b128 v[232:235], v184 offset:41824
	ds_read_b128 v[236:239], v184 offset:46432
	ds_read_b128 v[240:243], v184 offset:51040
	v_pk_add_f32 v[88:89], v[190:191], v[88:89]
	v_cvt_pk_bf16_f32 v244, v176, v177
	v_cvt_pk_bf16_f32 v245, v186, v187
	v_cvt_pk_bf16_f32 v246, v188, v189
	v_cvt_pk_bf16_f32 v247, v190, v191
	s_waitcnt lgkmcnt(7)
	s_nop 0
	v_mfma_f32_32x32x16_bf16 v[64:79], v[2:5], v[244:247], v[64:79]
	v_exp_f32_e32 v194, v80
	v_exp_f32_e32 v195, v81
	s_waitcnt lgkmcnt(6)
	v_mfma_f32_32x32x16_bf16 v[48:63], v[6:9], v[244:247], v[48:63]
	v_exp_f32_e32 v196, v82
	v_exp_f32_e32 v197, v83
	v_pk_add_f32 v[88:89], v[194:195], v[88:89]
	s_waitcnt lgkmcnt(5)
	v_mfma_f32_32x32x16_bf16 v[32:47], v[10:13], v[244:247], v[32:47]
	v_exp_f32_e32 v198, v84
	v_exp_f32_e32 v199, v85
	v_pk_add_f32 v[88:89], v[196:197], v[88:89]
	s_waitcnt lgkmcnt(4)
	v_mfma_f32_32x32x16_bf16 v[16:31], v[218:221], v[244:247], v[16:31]
	v_exp_f32_e32 v14, v14
	v_exp_f32_e32 v15, v15
	v_pk_add_f32 v[88:89], v[198:199], v[88:89]
	s_nop 0
	v_pk_add_f32 v[88:89], v[14:15], v[88:89]
	v_cvt_pk_bf16_f32 v248, v194, v195
	v_cvt_pk_bf16_f32 v249, v196, v197
	v_cvt_pk_bf16_f32 v250, v198, v199
	v_cvt_pk_bf16_f32 v251, v14, v15
	v_add_f32_e32 v88, v88, v89
	s_waitcnt lgkmcnt(3)
	v_add_f32_e32 v0, v0, v88
	v_mfma_f32_32x32x16_bf16 v[64:79], v[228:231], v[248:251], v[64:79]
	s_waitcnt lgkmcnt(2)
	v_mfma_f32_32x32x16_bf16 v[48:63], v[232:235], v[248:251], v[48:63]
	s_waitcnt lgkmcnt(1)
	v_mfma_f32_32x32x16_bf16 v[32:47], v[236:239], v[248:251], v[32:47]
	s_waitcnt lgkmcnt(0)
	v_mfma_f32_32x32x16_bf16 v[16:31], v[240:243], v[248:251], v[16:31]
	s_cmp_eq_u32 s2, 0
	s_cbranch_scc0 .LBB0_639

; template <int DVT, bool FOX>
; DI void attn_step(const char* kb, const bf16x8 (&qf)[4], f32x16 (&o)[DVT], float& m, float& l, const bool diag, const int j, const int tq, const int r, const int hh) {
;     ...
;   f32x2 ls2 = {0.f, 0.f};
; #pragma unroll
;   for (int kt = 0; kt < 2; ++kt)
; #pragma unroll
;     for (int i = 0; i < 8; ++i) {
;       f32x2 pv = {__builtin_amdgcn_exp2f(st[kt][2 * i]), __builtin_amdgcn_exp2f(st[kt][2 * i + 1])};
;       st[kt][2 * i] = pv[0]; st[kt][2 * i + 1] = pv[1];
;       ls2 = ls2 + pv;
;     }
;   l += ls2[0] + ls2[1];
;   __builtin_amdgcn_sched_barrier(0);
;     ...
;   A_PVGROUP(0, va, vn); A_PVGROUP(1, vn, va); A_PVGROUP(2, va, vn); A_PVGROUP(3, vn, va);
.LBB0_663:
	v_exp_f32_e32 v110, v168
	v_exp_f32_e32 v111, v169
	v_exp_f32_e32 v168, v170
	v_exp_f32_e32 v169, v171
	v_exp_f32_e32 v170, v172
	v_exp_f32_e32 v171, v173
	v_exp_f32_e32 v172, v174
	v_exp_f32_e32 v173, v175
	ds_read_b128 v[228:231], v177 offset:9248
	ds_read_b128 v[232:235], v177 offset:13856
	ds_read_b128 v[236:239], v177 offset:18464
	ds_read_b128 v[240:243], v177 offset:23072
	v_pk_add_f32 v[88:89], v[110:111], 0 op_sel_hi:[1,0]
	s_nop 0
	v_pk_add_f32 v[88:89], v[168:169], v[88:89]
	s_nop 0
	v_pk_add_f32 v[88:89], v[170:171], v[88:89]
	s_nop 0
	v_pk_add_f32 v[88:89], v[172:173], v[88:89]
	v_cvt_pk_bf16_f32 v244, v110, v111
	v_cvt_pk_bf16_f32 v245, v168, v169
	v_cvt_pk_bf16_f32 v246, v170, v171
	v_cvt_pk_bf16_f32 v247, v172, v173
	s_waitcnt lgkmcnt(7)
	s_nop 0
	v_mfma_f32_32x32x16_bf16 v[64:79], v[152:155], v[244:247], v[64:79]
	v_exp_f32_e32 v102, v102
	v_exp_f32_e32 v103, v103
	s_waitcnt lgkmcnt(6)
	v_mfma_f32_32x32x16_bf16 v[48:63], v[10:13], v[244:247], v[48:63]
	v_exp_f32_e32 v104, v104
	v_exp_f32_e32 v105, v105
	v_pk_add_f32 v[88:89], v[102:103], v[88:89]
	s_waitcnt lgkmcnt(5)
	v_mfma_f32_32x32x16_bf16 v[32:47], v[6:9], v[244:247], v[32:47]
	v_exp_f32_e32 v106, v106
	v_exp_f32_e32 v107, v107
	v_pk_add_f32 v[88:89], v[104:105], v[88:89]
	s_waitcnt lgkmcnt(4)
	v_mfma_f32_32x32x16_bf16 v[16:31], v[2:5], v[244:247], v[16:31]
	v_exp_f32_e32 v108, v108
	v_exp_f32_e32 v109, v109
	v_pk_add_f32 v[88:89], v[106:107], v[88:89]
	ds_read_b128 v[2:5], v177 offset:9280
	ds_read_b128 v[6:9], v177 offset:13888
	ds_read_b128 v[10:13], v177 offset:18496
	ds_read_b128 v[218:221], v177 offset:23104
	v_pk_add_f32 v[88:89], v[108:109], v[88:89]
	v_cvt_pk_bf16_f32 v248, v102, v103
	v_cvt_pk_bf16_f32 v249, v104, v105
	v_cvt_pk_bf16_f32 v250, v106, v107
	v_cvt_pk_bf16_f32 v251, v108, v109
	s_waitcnt lgkmcnt(7)
	s_nop 0
	v_mfma_f32_32x32x16_bf16 v[64:79], v[228:231], v[248:251], v[64:79]
	v_exp_f32_e32 v174, v96
	v_exp_f32_e32 v175, v97
	s_waitcnt lgkmcnt(6)
	v_mfma_f32_32x32x16_bf16 v[48:63], v[232:235], v[248:251], v[48:63]
	v_exp_f32_e32 v184, v98
	v_exp_f32_e32 v185, v99
	v_pk_add_f32 v[88:89], v[174:175], v[88:89]
	s_waitcnt lgkmcnt(5)
	v_mfma_f32_32x32x16_bf16 v[32:47], v[236:239], v[248:251], v[32:47]
	v_exp_f32_e32 v186, v100
	v_exp_f32_e32 v187, v101
	v_pk_add_f32 v[88:89], v[184:185], v[88:89]
	s_waitcnt lgkmcnt(4)
	v_mfma_f32_32x32x16_bf16 v[16:31], v[240:243], v[248:251], v[16:31]
	v_exp_f32_e32 v188, v86
	v_exp_f32_e32 v189, v87
	v_pk_add_f32 v[88:89], v[186:187], v[88:89]
	ds_read_b128 v[228:231], v177 offset:9312
	ds_read_b128 v[232:235], v177 offset:13920
	ds_read_b128 v[236:239], v177 offset:18528
	ds_read_b128 v[240:243], v177 offset:23136
	v_pk_add_f32 v[88:89], v[188:189], v[88:89]
	v_cvt_pk_bf16_f32 v244, v174, v175
	v_cvt_pk_bf16_f32 v245, v184, v185
	v_cvt_pk_bf16_f32 v246, v186, v187
	v_cvt_pk_bf16_f32 v247, v188, v189
	s_waitcnt lgkmcnt(7)
	s_nop 0
	v_mfma_f32_32x32x16_bf16 v[64:79], v[2:5], v[244:247], v[64:79]
	v_exp_f32_e32 v190, v80
	v_exp_f32_e32 v191, v81
	s_waitcnt lgkmcnt(6)
	v_mfma_f32_32x32x16_bf16 v[48:63], v[6:9], v[244:247], v[48:63]
	v_exp_f32_e32 v194, v82
	v_exp_f32_e32 v195, v83
	v_pk_add_f32 v[88:89], v[190:191], v[88:89]
	s_waitcnt lgkmcnt(5)
	v_mfma_f32_32x32x16_bf16 v[32:47], v[10:13], v[244:247], v[32:47]
	v_exp_f32_e32 v196, v84
	v_exp_f32_e32 v197, v85
	v_pk_add_f32 v[88:89], v[194:195], v[88:89]
	s_waitcnt lgkmcnt(4)
	v_mfma_f32_32x32x16_bf16 v[16:31], v[218:221], v[244:247], v[16:31]
	v_exp_f32_e32 v14, v14
	v_exp_f32_e32 v15, v15
	v_pk_add_f32 v[88:89], v[196:197], v[88:89]
	s_nop 0
	v_pk_add_f32 v[88:89], v[14:15], v[88:89]
	v_cvt_pk_bf16_f32 v248, v190, v191
	v_cvt_pk_bf16_f32 v249, v194, v195
	v_cvt_pk_bf16_f32 v250, v196, v197
	v_cvt_pk_bf16_f32 v251, v14, v15
	v_add_f32_e32 v88, v88, v89
	s_waitcnt lgkmcnt(3)
	v_add_f32_e32 v0, v0, v88
	v_mfma_f32_32x32x16_bf16 v[64:79], v[228:231], v[248:251], v[64:79]
	s_waitcnt lgkmcnt(2)
	v_mfma_f32_32x32x16_bf16 v[48:63], v[232:235], v[248:251], v[48:63]
	s_waitcnt lgkmcnt(1)
	v_mfma_f32_32x32x16_bf16 v[32:47], v[236:239], v[248:251], v[32:47]
	s_waitcnt lgkmcnt(0)
	v_mfma_f32_32x32x16_bf16 v[16:31], v[240:243], v[248:251], v[16:31]

; template <int DVT, bool FOX>
; DI void attn_step(const char* kb, const bf16x8 (&qf)[4], f32x16 (&o)[DVT], float& m, float& l, const bool diag, const int j, const int tq, const int r, const int hh) {
;     ...
;   f32x2 ls2 = {0.f, 0.f};
; #pragma unroll
;   for (int kt = 0; kt < 2; ++kt)
; #pragma unroll
;     for (int i = 0; i < 8; ++i) {
;       f32x2 pv = {__builtin_amdgcn_exp2f(st[kt][2 * i]), __builtin_amdgcn_exp2f(st[kt][2 * i + 1])};
;       st[kt][2 * i] = pv[0]; st[kt][2 * i + 1] = pv[1];
;       ls2 = ls2 + pv;
;     }
;   l += ls2[0] + ls2[1];
;   __builtin_amdgcn_sched_barrier(0);
;     ...
;   A_PVGROUP(0, va, vn); A_PVGROUP(1, vn, va); A_PVGROUP(2, va, vn); A_PVGROUP(3, vn, va);
.LBB0_670:
	v_exp_f32_e32 v110, v168
	v_exp_f32_e32 v111, v169
	v_exp_f32_e32 v168, v170
	v_exp_f32_e32 v169, v171
	v_exp_f32_e32 v170, v172
	v_exp_f32_e32 v171, v173
	v_exp_f32_e32 v172, v174
	v_exp_f32_e32 v173, v175
	ds_read_b128 v[228:231], v177 offset:37152
	ds_read_b128 v[232:235], v177 offset:41760
	ds_read_b128 v[236:239], v177 offset:46368
	ds_read_b128 v[240:243], v177 offset:50976
	v_pk_add_f32 v[88:89], v[110:111], 0 op_sel_hi:[1,0]
	s_nop 0
	v_pk_add_f32 v[88:89], v[168:169], v[88:89]
	s_nop 0
	v_pk_add_f32 v[88:89], v[170:171], v[88:89]
	s_nop 0
	v_pk_add_f32 v[88:89], v[172:173], v[88:89]
	v_cvt_pk_bf16_f32 v244, v110, v111
	v_cvt_pk_bf16_f32 v245, v168, v169
	v_cvt_pk_bf16_f32 v246, v170, v171
	v_cvt_pk_bf16_f32 v247, v172, v173
	s_waitcnt lgkmcnt(7)
	s_nop 0
	v_mfma_f32_32x32x16_bf16 v[64:79], v[152:155], v[244:247], v[64:79]
	v_exp_f32_e32 v102, v102
	v_exp_f32_e32 v103, v103
	s_waitcnt lgkmcnt(6)
	v_mfma_f32_32x32x16_bf16 v[48:63], v[10:13], v[244:247], v[48:63]
	v_exp_f32_e32 v104, v104
	v_exp_f32_e32 v105, v105
	v_pk_add_f32 v[88:89], v[102:103], v[88:89]
	s_waitcnt lgkmcnt(5)
	v_mfma_f32_32x32x16_bf16 v[32:47], v[6:9], v[244:247], v[32:47]
	v_exp_f32_e32 v106, v106
	v_exp_f32_e32 v107, v107
	v_pk_add_f32 v[88:89], v[104:105], v[88:89]
	s_waitcnt lgkmcnt(4)
	v_mfma_f32_32x32x16_bf16 v[16:31], v[2:5], v[244:247], v[16:31]
	v_exp_f32_e32 v108, v108
	v_exp_f32_e32 v109, v109
	v_pk_add_f32 v[88:89], v[106:107], v[88:89]
	ds_read_b128 v[2:5], v177 offset:37184
	ds_read_b128 v[6:9], v177 offset:41792
	ds_read_b128 v[10:13], v177 offset:46400
	ds_read_b128 v[218:221], v177 offset:51008
	v_pk_add_f32 v[88:89], v[108:109], v[88:89]
	v_cvt_pk_bf16_f32 v248, v102, v103
	v_cvt_pk_bf16_f32 v249, v104, v105
	v_cvt_pk_bf16_f32 v250, v106, v107
	v_cvt_pk_bf16_f32 v251, v108, v109
	s_waitcnt lgkmcnt(7)
	s_nop 0
	v_mfma_f32_32x32x16_bf16 v[64:79], v[228:231], v[248:251], v[64:79]
	v_exp_f32_e32 v174, v96
	v_exp_f32_e32 v175, v97
	s_waitcnt lgkmcnt(6)
	v_mfma_f32_32x32x16_bf16 v[48:63], v[232:235], v[248:251], v[48:63]
	v_exp_f32_e32 v184, v98
	v_exp_f32_e32 v185, v99
	v_pk_add_f32 v[88:89], v[174:175], v[88:89]
	s_waitcnt lgkmcnt(5)
	v_mfma_f32_32x32x16_bf16 v[32:47], v[236:239], v[248:251], v[32:47]
	v_exp_f32_e32 v186, v100
	v_exp_f32_e32 v187, v101
	v_pk_add_f32 v[88:89], v[184:185], v[88:89]
	s_waitcnt lgkmcnt(4)
	v_mfma_f32_32x32x16_bf16 v[16:31], v[240:243], v[248:251], v[16:31]
	v_exp_f32_e32 v188, v86
	v_exp_f32_e32 v189, v87
	v_pk_add_f32 v[88:89], v[186:187], v[88:89]
	ds_read_b128 v[228:231], v177 offset:37216
	ds_read_b128 v[232:235], v177 offset:41824
	ds_read_b128 v[236:239], v177 offset:46432
	ds_read_b128 v[240:243], v177 offset:51040
	v_pk_add_f32 v[88:89], v[188:189], v[88:89]
	v_cvt_pk_bf16_f32 v244, v174, v175
	v_cvt_pk_bf16_f32 v245, v184, v185
	v_cvt_pk_bf16_f32 v246, v186, v187
	v_cvt_pk_bf16_f32 v247, v188, v189
	s_waitcnt lgkmcnt(7)
	s_nop 0
	v_mfma_f32_32x32x16_bf16 v[64:79], v[2:5], v[244:247], v[64:79]
	v_exp_f32_e32 v190, v80
	v_exp_f32_e32 v191, v81
	s_waitcnt lgkmcnt(6)
	v_mfma_f32_32x32x16_bf16 v[48:63], v[6:9], v[244:247], v[48:63]
	v_exp_f32_e32 v194, v82
	v_exp_f32_e32 v195, v83
	v_pk_add_f32 v[88:89], v[190:191], v[88:89]
	s_waitcnt lgkmcnt(5)
	v_mfma_f32_32x32x16_bf16 v[32:47], v[10:13], v[244:247], v[32:47]
	v_exp_f32_e32 v196, v84
	v_exp_f32_e32 v197, v85
	v_pk_add_f32 v[88:89], v[194:195], v[88:89]
	s_waitcnt lgkmcnt(4)
	v_mfma_f32_32x32x16_bf16 v[16:31], v[218:221], v[244:247], v[16:31]
	v_exp_f32_e32 v14, v14
	v_exp_f32_e32 v15, v15
	v_pk_add_f32 v[88:89], v[196:197], v[88:89]
	s_nop 0
	v_pk_add_f32 v[88:89], v[14:15], v[88:89]
	v_cvt_pk_bf16_f32 v248, v190, v191
	v_cvt_pk_bf16_f32 v249, v194, v195
	v_cvt_pk_bf16_f32 v250, v196, v197
	v_cvt_pk_bf16_f32 v251, v14, v15
	v_add_f32_e32 v88, v88, v89
	s_waitcnt lgkmcnt(3)
	v_add_f32_e32 v0, v0, v88
	v_mfma_f32_32x32x16_bf16 v[64:79], v[228:231], v[248:251], v[64:79]
	s_waitcnt lgkmcnt(2)
	v_mfma_f32_32x32x16_bf16 v[48:63], v[232:235], v[248:251], v[48:63]
	s_waitcnt lgkmcnt(1)
	v_mfma_f32_32x32x16_bf16 v[32:47], v[236:239], v[248:251], v[32:47]
	s_waitcnt lgkmcnt(0)
	v_mfma_f32_32x32x16_bf16 v[16:31], v[240:243], v[248:251], v[16:31]
	s_cmp_eq_u32 s27, 0
	s_cbranch_scc0 .LBB0_657
